# 128x128 GEMM k-loops (phase 1 z/kvm, phase 4 gate) use v_mfma_f32_16x16x32_bf16 (same bf16 operands/f32 accumulate, bit-identical) + in-place permlane16/32 swap back to the 32x32 accumulator layout
# speedup vs baseline: 1.0219x; 1.0052x over previous
.LBB0_123:
	s_lshl_b32 s2, s20, 10
	s_add_i32 s2, s15, s2
	v_readlane_b32 s72, v250, 53
	v_mov_b32_e32 v60, v200
	s_lshl_b64 s[8:9], s[2:3], 11
	v_readlane_b32 s80, v250, 61
	v_readlane_b32 s81, v250, 62
	v_ashrrev_i32_e32 v36, 3, v60
	v_lshlrev_b32_e32 v0, 3, v60
	s_add_u32 s8, s80, s8
	v_and_b32_e32 v181, 56, v0
	v_add_u32_e32 v42, 32, v36
	v_add_u32_e32 v48, 64, v36
	v_add_u32_e32 v54, 0x60, v36
	s_addc_u32 s9, s81, s9
	v_lshlrev_b32_e32 v196, 1, v181
	v_ashrrev_i32_e32 v37, 31, v36
	v_ashrrev_i32_e32 v43, 31, v42
	v_ashrrev_i32_e32 v49, 31, v48
	v_ashrrev_i32_e32 v55, 31, v54
	v_lshl_add_u64 v[128:129], s[6:7], 0, v[196:197]
	v_lshl_add_u64 v[130:131], s[8:9], 0, v[196:197]
	v_lshlrev_b64 v[132:133], 11, v[36:37]
	v_lshlrev_b64 v[134:135], 11, v[42:43]
	v_lshlrev_b64 v[136:137], 11, v[48:49]
	v_lshlrev_b64 v[138:139], 11, v[54:55]
	v_lshl_add_u64 v[38:39], v[128:129], 0, v[132:133]
	v_lshl_add_u64 v[40:41], v[130:131], 0, v[132:133]
	v_lshl_add_u64 v[44:45], v[128:129], 0, v[134:135]
	v_lshl_add_u64 v[46:47], v[130:131], 0, v[134:135]
	v_lshl_add_u64 v[50:51], v[128:129], 0, v[136:137]
	v_lshl_add_u64 v[52:53], v[130:131], 0, v[136:137]
	v_lshl_add_u64 v[56:57], v[128:129], 0, v[138:139]
	v_lshl_add_u64 v[58:59], v[130:131], 0, v[138:139]
	v_and_b32_e32 v242, 63, v200
	v_readfirstlane_b32 s41, v200
	v_lshrrev_b32_e32 v243, 3, v242
	v_and_b32_e32 v244, 7, v242
	v_lshrrev_b32_e32 v246, 4, v242
	s_lshr_b32 s41, s41, 6
	v_xor_b32_e32 v244, v244, v246
	v_lshlrev_b32_e32 v244, 4, v244
	v_xor_b32_e32 v246, 64, v244
	s_lshl_b32 s46, s41, 5
	v_add_u32_e32 v243, s46, v243
	v_lshlrev_b32_e32 v247, 11, v243
	v_add_u32_e32 v186, v247, v244
	v_add_u32_e32 v187, v247, v246
	v_add_u32_e32 v188, 0x8000, v186
	v_add_u32_e32 v189, 0x8000, v187
	v_add_u32_e32 v187, 0x4000, v187
	v_add_u32_e32 v189, 0x4000, v189
	v_and_b32_e32 v243, 15, v242
	v_lshrrev_b32_e32 v244, 4, v242
	v_bfe_u32 v246, v242, 1, 3
	v_xor_b32_e32 v244, v244, v246
	v_lshlrev_b32_e32 v244, 4, v244
	v_lshl_add_u32 v244, v243, 7, v244
	s_lshr_b32 s46, s41, 1
	s_lshl_b32 s46, s46, 13
	v_add_u32_e32 v190, s46, v244
	s_and_b32 s46, s41, 1
	s_lshl_b32 s46, s46, 13
	s_add_u32 s46, s46, 0x4000
	v_add_u32_e32 v194, s46, v244
	v_xor_b32_e32 v191, 64, v190
	v_xor_b32_e32 v201, 64, v194
	v_xor_b32_e32 v192, 64, v190
	v_xor_b32_e32 v206, 64, v194
	v_xor_b32_e32 v193, 96, v190
	v_xor_b32_e32 v214, 96, v194
	s_lshl_b32 s46, s41, 12
	s_add_u32 s47, s46, 0x4000
	s_mov_b32 s42, s6
	s_mov_b32 s43, s7
	s_mov_b32 s44, s8
	s_mov_b32 s45, s9
	s_add_u32 m0, s46, 0x0
	s_nop 0
	global_load_lds_dwordx4 v186, s[42:43]
	s_add_u32 m0, m0, 0x400
	s_nop 0
	global_load_lds_dwordx4 v187, s[42:43]
	s_add_u32 m0, m0, 0x400
	s_nop 0
	global_load_lds_dwordx4 v188, s[42:43]
	s_add_u32 m0, m0, 0x400
	s_nop 0
	global_load_lds_dwordx4 v189, s[42:43]
	s_add_u32 m0, s46, 0x4000
	s_nop 0
	global_load_lds_dwordx4 v186, s[44:45]
	s_add_u32 m0, m0, 0x400
	s_nop 0
	global_load_lds_dwordx4 v187, s[44:45]
	s_add_u32 m0, m0, 0x400
	s_nop 0
	global_load_lds_dwordx4 v188, s[44:45]
	s_add_u32 m0, m0, 0x400
	s_nop 0
	global_load_lds_dwordx4 v189, s[44:45]
	s_add_u32 s42, s42, 128
	s_addc_u32 s43, s43, 0
	s_add_u32 s44, s44, 128
	s_addc_u32 s45, s45, 0
	v_and_b32_e32 v61, 31, v60
	v_lshrrev_b32_e32 v62, 1, v60
	v_and_b32_e32 v60, 0x5f, v60
	s_movk_i32 s2, 0x90
	s_mov_b32 s26, 0xfffffc0
	v_and_or_b32 v61, v62, s26, v61
	v_and_b32_e32 v62, 16, v62
	v_mad_u32_u24 v60, v60, s2, 0
	v_mul_lo_u32 v63, v36, s2
	v_mul_lo_u32 v61, v61, s2
	v_add_u32_e32 v182, v60, v62
	v_add_u32_e32 v60, 0, v196
	v_lshlrev_b64 v[36:37], 10, v[36:37]
	v_add_u32_e32 v96, 0x1200, v63
	v_lshlrev_b64 v[42:43], 10, v[42:43]
	v_lshlrev_b64 v[48:49], 10, v[48:49]
	v_lshlrev_b64 v[54:55], 10, v[54:55]
	v_add_u32_e32 v38, 0, v61
	v_add_u32_e32 v183, v60, v63
	s_mov_b32 s21, 0
	s_movk_i32 s22, 0x80
	v_mov_b32_e32 v0, 0
	v_mov_b32_e32 v1, v172
	v_mov_b32_e32 v2, v172
	v_mov_b32_e32 v3, v172
	v_lshlrev_b64 v[140:141], 1, v[36:37]
	v_add_u32_e32 v184, v60, v96
	v_lshlrev_b64 v[142:143], 1, v[42:43]
	v_lshlrev_b64 v[144:145], 1, v[48:49]
	v_lshlrev_b64 v[146:147], 1, v[54:55]
	v_add_u32_e32 v185, v38, v62
	v_mov_b32_e32 v36, v172
	v_mov_b32_e32 v37, v172
	v_mov_b32_e32 v38, v172
	v_mov_b32_e32 v39, v172
	v_mov_b32_e32 v40, v172
	v_mov_b32_e32 v41, v172
	v_mov_b32_e32 v42, v172
	v_mov_b32_e32 v43, v172
	v_mov_b32_e32 v44, v172
	v_mov_b32_e32 v45, v172
	v_mov_b32_e32 v46, v172
	v_mov_b32_e32 v4, v172
	v_mov_b32_e32 v5, v172
	v_mov_b32_e32 v6, v172
	v_mov_b32_e32 v7, v172
	v_mov_b32_e32 v8, v172
	v_mov_b32_e32 v9, v172
	v_mov_b32_e32 v10, v172
	v_mov_b32_e32 v11, v172
	v_mov_b32_e32 v12, v172
	v_mov_b32_e32 v13, v172
	v_mov_b32_e32 v14, v172
	v_mov_b32_e32 v15, v172
	v_mov_b32_e32 v16, 0
	v_mov_b32_e32 v17, v172
	v_mov_b32_e32 v18, v172
	v_mov_b32_e32 v19, v172
	v_mov_b32_e32 v20, v172
	v_mov_b32_e32 v21, v172
	v_mov_b32_e32 v22, v172
	v_mov_b32_e32 v23, v172
	v_mov_b32_e32 v24, v172
	v_mov_b32_e32 v25, v172
	v_mov_b32_e32 v26, v172
	v_mov_b32_e32 v27, v172
	v_mov_b32_e32 v28, v172
	v_mov_b32_e32 v29, v172
	v_mov_b32_e32 v30, v172
	v_mov_b32_e32 v31, v172
	v_mov_b32_e32 v32, 0
	v_mov_b32_e32 v33, v172
	v_mov_b32_e32 v34, v172
	v_mov_b32_e32 v35, v172
	v_mov_b32_e32 v47, v172
	v_mov_b32_e32 v48, 0
	v_mov_b32_e32 v49, v172
	v_mov_b32_e32 v50, v172
	v_mov_b32_e32 v51, v172
	v_mov_b32_e32 v52, v172
	v_mov_b32_e32 v53, v172
	v_mov_b32_e32 v54, v172
	v_mov_b32_e32 v55, v172
	v_mov_b32_e32 v56, v172
	v_mov_b32_e32 v57, v172
	v_mov_b32_e32 v58, v172
	v_mov_b32_e32 v59, v172
	v_mov_b32_e32 v60, v172
	v_mov_b32_e32 v61, v172
	v_mov_b32_e32 v62, v172
	v_mov_b32_e32 v63, v172
	v_readlane_b32 s73, v250, 54
	v_readlane_b32 s74, v250, 55
	v_readlane_b32 s75, v250, 56
	v_readlane_b32 s76, v250, 57
	v_readlane_b32 s77, v250, 58
	v_readlane_b32 s78, v250, 59
	v_readlane_b32 s79, v250, 60
	v_readlane_b32 s82, v250, 63
	v_readlane_b32 s83, v249, 0
	v_readlane_b32 s84, v249, 1
	v_readlane_b32 s85, v249, 2
	v_readlane_b32 s86, v249, 3
	v_readlane_b32 s87, v249, 4
	s_mov_b32 s49, 0x8000
	s_waitcnt vmcnt(0)
	s_waitcnt lgkmcnt(0)
	v_readlane_b32 s41, v251, 5
	s_nop 0
	s_bitcmp1_b32 s41, 5
	s_cbranch_scc0 .Lnoprio_5
	s_setprio 2

.LBB0_125:
	ds_read_b128 v[64:67], v194
	ds_read_b128 v[68:71], v190
	ds_read_b128 v[72:75], v194 offset:2048
	ds_read_b128 v[76:79], v190 offset:2048
	ds_read_b128 v[80:83], v194 offset:4096
	ds_read_b128 v[84:87], v194 offset:6144
	ds_read_b128 v[88:91], v190 offset:4096
	ds_read_b128 v[92:95], v190 offset:6144
	ds_read_b128 v[96:99], v201
	ds_read_b128 v[100:103], v191
	ds_read_b128 v[104:107], v201 offset:2048
	ds_read_b128 v[108:111], v191 offset:2048
	ds_read_b128 v[112:115], v201 offset:4096
	ds_read_b128 v[116:119], v201 offset:6144
	ds_read_b128 v[120:123], v191 offset:4096
	ds_read_b128 v[124:127], v191 offset:6144
	s_add_u32 m0, s46, s49
	s_nop 0
	global_load_lds_dwordx4 v186, s[42:43]
	s_add_u32 m0, m0, 0x400
	s_nop 0
	global_load_lds_dwordx4 v187, s[42:43]
	s_add_u32 m0, m0, 0x400
	s_nop 0
	global_load_lds_dwordx4 v188, s[42:43]
	s_add_u32 m0, m0, 0x400
	s_nop 0
	global_load_lds_dwordx4 v189, s[42:43]
	s_add_u32 m0, s47, s49
	s_nop 0
	global_load_lds_dwordx4 v186, s[44:45]
	s_add_u32 m0, m0, 0x400
	s_nop 0
	global_load_lds_dwordx4 v187, s[44:45]
	s_add_u32 m0, m0, 0x400
	s_nop 0
	global_load_lds_dwordx4 v188, s[44:45]
	s_add_u32 m0, m0, 0x400
	s_nop 0
	global_load_lds_dwordx4 v189, s[44:45]
	s_waitcnt lgkmcnt(14)
	v_mfma_f32_16x16x32_bf16 v[48:51], v[64:67], v[68:71], v[48:51]
	s_waitcnt lgkmcnt(13)
	v_mfma_f32_16x16x32_bf16 v[56:59], v[72:75], v[68:71], v[56:59]
	s_waitcnt lgkmcnt(12)
	v_mfma_f32_16x16x32_bf16 v[52:55], v[64:67], v[76:79], v[52:55]
	v_mfma_f32_16x16x32_bf16 v[60:63], v[72:75], v[76:79], v[60:63]
	s_waitcnt lgkmcnt(11)
	v_mfma_f32_16x16x32_bf16 v[32:35], v[80:83], v[68:71], v[32:35]
	v_mfma_f32_16x16x32_bf16 v[36:39], v[80:83], v[76:79], v[36:39]
	s_waitcnt lgkmcnt(10)
	v_mfma_f32_16x16x32_bf16 v[40:43], v[84:87], v[68:71], v[40:43]
	v_mfma_f32_16x16x32_bf16 v[44:47], v[84:87], v[76:79], v[44:47]
	s_waitcnt lgkmcnt(9)
	v_mfma_f32_16x16x32_bf16 v[16:19], v[64:67], v[88:91], v[16:19]
	v_mfma_f32_16x16x32_bf16 v[24:27], v[72:75], v[88:91], v[24:27]
	v_mfma_f32_16x16x32_bf16 v[0:3], v[80:83], v[88:91], v[0:3]
	v_mfma_f32_16x16x32_bf16 v[8:11], v[84:87], v[88:91], v[8:11]
	s_waitcnt lgkmcnt(8)
	v_mfma_f32_16x16x32_bf16 v[20:23], v[64:67], v[92:95], v[20:23]
	v_mfma_f32_16x16x32_bf16 v[28:31], v[72:75], v[92:95], v[28:31]
	v_mfma_f32_16x16x32_bf16 v[4:7], v[80:83], v[92:95], v[4:7]
	v_mfma_f32_16x16x32_bf16 v[12:15], v[84:87], v[92:95], v[12:15]
	s_waitcnt lgkmcnt(6)
	v_mfma_f32_16x16x32_bf16 v[48:51], v[96:99], v[100:103], v[48:51]
	s_waitcnt lgkmcnt(5)
	v_mfma_f32_16x16x32_bf16 v[56:59], v[104:107], v[100:103], v[56:59]
	s_waitcnt lgkmcnt(4)
	v_mfma_f32_16x16x32_bf16 v[52:55], v[96:99], v[108:111], v[52:55]
	v_mfma_f32_16x16x32_bf16 v[60:63], v[104:107], v[108:111], v[60:63]
	s_waitcnt lgkmcnt(3)
	v_mfma_f32_16x16x32_bf16 v[32:35], v[112:115], v[100:103], v[32:35]
	v_mfma_f32_16x16x32_bf16 v[36:39], v[112:115], v[108:111], v[36:39]
	s_waitcnt lgkmcnt(2)
	v_mfma_f32_16x16x32_bf16 v[40:43], v[116:119], v[100:103], v[40:43]
	v_mfma_f32_16x16x32_bf16 v[44:47], v[116:119], v[108:111], v[44:47]
	s_waitcnt lgkmcnt(1)
	v_mfma_f32_16x16x32_bf16 v[16:19], v[96:99], v[120:123], v[16:19]
	v_mfma_f32_16x16x32_bf16 v[24:27], v[104:107], v[120:123], v[24:27]
	v_mfma_f32_16x16x32_bf16 v[0:3], v[112:115], v[120:123], v[0:3]
	v_mfma_f32_16x16x32_bf16 v[8:11], v[116:119], v[120:123], v[8:11]
	s_waitcnt lgkmcnt(0)
	v_mfma_f32_16x16x32_bf16 v[20:23], v[96:99], v[124:127], v[20:23]
	v_mfma_f32_16x16x32_bf16 v[28:31], v[104:107], v[124:127], v[28:31]
	v_mfma_f32_16x16x32_bf16 v[4:7], v[112:115], v[124:127], v[4:7]
	v_mfma_f32_16x16x32_bf16 v[12:15], v[116:119], v[124:127], v[12:15]
	v_xor_b32_e32 v190, 0x8000, v190
	v_xor_b32_e32 v191, 0x8000, v191
	v_xor_b32_e32 v194, 0x8000, v194
	v_xor_b32_e32 v201, 0x8000, v201
	s_xor_b32 s49, s49, 0x8000
	s_add_u32 s42, s42, 128
	s_addc_u32 s43, s43, 0
	s_add_u32 s44, s44, 128
	s_addc_u32 s45, s45, 0
	s_add_u32 s21, s21, 1
	s_waitcnt vmcnt(0)
	s_cmp_lt_u32 s21, 15
	s_barrier
	s_cbranch_scc1 .LBB0_125
.Lp4g_tail:
	ds_read_b128 v[64:67], v194
	ds_read_b128 v[68:71], v190
	ds_read_b128 v[72:75], v194 offset:2048
	ds_read_b128 v[76:79], v190 offset:2048
	ds_read_b128 v[80:83], v194 offset:4096
	ds_read_b128 v[84:87], v194 offset:6144
	ds_read_b128 v[88:91], v190 offset:4096
	ds_read_b128 v[92:95], v190 offset:6144
	ds_read_b128 v[96:99], v201
	ds_read_b128 v[100:103], v191
	ds_read_b128 v[104:107], v201 offset:2048
	ds_read_b128 v[108:111], v191 offset:2048
	ds_read_b128 v[112:115], v201 offset:4096
	ds_read_b128 v[116:119], v201 offset:6144
	ds_read_b128 v[120:123], v191 offset:4096
	ds_read_b128 v[124:127], v191 offset:6144
	s_waitcnt lgkmcnt(14)
	v_mfma_f32_16x16x32_bf16 v[48:51], v[64:67], v[68:71], v[48:51]
	s_waitcnt lgkmcnt(13)
	v_mfma_f32_16x16x32_bf16 v[56:59], v[72:75], v[68:71], v[56:59]
	s_waitcnt lgkmcnt(12)
	v_mfma_f32_16x16x32_bf16 v[52:55], v[64:67], v[76:79], v[52:55]
	v_mfma_f32_16x16x32_bf16 v[60:63], v[72:75], v[76:79], v[60:63]
	s_waitcnt lgkmcnt(11)
	v_mfma_f32_16x16x32_bf16 v[32:35], v[80:83], v[68:71], v[32:35]
	v_mfma_f32_16x16x32_bf16 v[36:39], v[80:83], v[76:79], v[36:39]
	s_waitcnt lgkmcnt(10)
	v_mfma_f32_16x16x32_bf16 v[40:43], v[84:87], v[68:71], v[40:43]
	v_mfma_f32_16x16x32_bf16 v[44:47], v[84:87], v[76:79], v[44:47]
	s_waitcnt lgkmcnt(9)
	v_mfma_f32_16x16x32_bf16 v[16:19], v[64:67], v[88:91], v[16:19]
	v_mfma_f32_16x16x32_bf16 v[24:27], v[72:75], v[88:91], v[24:27]
	v_mfma_f32_16x16x32_bf16 v[0:3], v[80:83], v[88:91], v[0:3]
	v_mfma_f32_16x16x32_bf16 v[8:11], v[84:87], v[88:91], v[8:11]
	s_waitcnt lgkmcnt(8)
	v_mfma_f32_16x16x32_bf16 v[20:23], v[64:67], v[92:95], v[20:23]
	v_mfma_f32_16x16x32_bf16 v[28:31], v[72:75], v[92:95], v[28:31]
	v_mfma_f32_16x16x32_bf16 v[4:7], v[80:83], v[92:95], v[4:7]
	v_mfma_f32_16x16x32_bf16 v[12:15], v[84:87], v[92:95], v[12:15]
	s_waitcnt lgkmcnt(6)
	v_mfma_f32_16x16x32_bf16 v[48:51], v[96:99], v[100:103], v[48:51]
	s_waitcnt lgkmcnt(5)
	v_mfma_f32_16x16x32_bf16 v[56:59], v[104:107], v[100:103], v[56:59]
	s_waitcnt lgkmcnt(4)
	v_mfma_f32_16x16x32_bf16 v[52:55], v[96:99], v[108:111], v[52:55]
	v_mfma_f32_16x16x32_bf16 v[60:63], v[104:107], v[108:111], v[60:63]
	s_waitcnt lgkmcnt(3)
	v_mfma_f32_16x16x32_bf16 v[32:35], v[112:115], v[100:103], v[32:35]
	v_mfma_f32_16x16x32_bf16 v[36:39], v[112:115], v[108:111], v[36:39]
	s_waitcnt lgkmcnt(2)
	v_mfma_f32_16x16x32_bf16 v[40:43], v[116:119], v[100:103], v[40:43]
	v_mfma_f32_16x16x32_bf16 v[44:47], v[116:119], v[108:111], v[44:47]
	s_waitcnt lgkmcnt(1)
	v_mfma_f32_16x16x32_bf16 v[16:19], v[96:99], v[120:123], v[16:19]
	v_mfma_f32_16x16x32_bf16 v[24:27], v[104:107], v[120:123], v[24:27]
	v_mfma_f32_16x16x32_bf16 v[0:3], v[112:115], v[120:123], v[0:3]
	v_mfma_f32_16x16x32_bf16 v[8:11], v[116:119], v[120:123], v[8:11]
	s_waitcnt lgkmcnt(0)
	v_mfma_f32_16x16x32_bf16 v[20:23], v[96:99], v[124:127], v[20:23]
	v_mfma_f32_16x16x32_bf16 v[28:31], v[104:107], v[124:127], v[28:31]
	v_mfma_f32_16x16x32_bf16 v[4:7], v[112:115], v[124:127], v[4:7]
	v_mfma_f32_16x16x32_bf16 v[12:15], v[116:119], v[124:127], v[12:15]
	v_xor_b32_e32 v190, 0x8000, v190
	v_xor_b32_e32 v191, 0x8000, v191
	v_xor_b32_e32 v194, 0x8000, v194
	v_xor_b32_e32 v201, 0x8000, v201
	s_add_u32 s21, s21, 1
	s_waitcnt vmcnt(0)
	s_cmp_lt_u32 s21, 16
	s_barrier
	s_nop 7
	s_nop 7
	v_permlane16_swap_b32_e32 v48, v52
	v_permlane16_swap_b32_e32 v49, v53
	v_permlane16_swap_b32_e32 v50, v54
	v_permlane16_swap_b32_e32 v51, v55
	v_permlane16_swap_b32_e32 v56, v60
	v_permlane16_swap_b32_e32 v57, v61
	v_permlane16_swap_b32_e32 v58, v62
	v_permlane16_swap_b32_e32 v59, v63
	v_permlane16_swap_b32_e32 v32, v36
	v_permlane16_swap_b32_e32 v33, v37
	v_permlane16_swap_b32_e32 v34, v38
	v_permlane16_swap_b32_e32 v35, v39
	v_permlane16_swap_b32_e32 v40, v44
	v_permlane16_swap_b32_e32 v41, v45
	v_permlane16_swap_b32_e32 v42, v46
	v_permlane16_swap_b32_e32 v43, v47
	v_permlane16_swap_b32_e32 v16, v20
	v_permlane16_swap_b32_e32 v17, v21
	v_permlane16_swap_b32_e32 v18, v22
	v_permlane16_swap_b32_e32 v19, v23
	v_permlane16_swap_b32_e32 v24, v28
	v_permlane16_swap_b32_e32 v25, v29
	v_permlane16_swap_b32_e32 v26, v30
	v_permlane16_swap_b32_e32 v27, v31
	v_permlane16_swap_b32_e32 v0, v4
	v_permlane16_swap_b32_e32 v1, v5
	v_permlane16_swap_b32_e32 v2, v6
	v_permlane16_swap_b32_e32 v3, v7
	v_permlane16_swap_b32_e32 v8, v12
	v_permlane16_swap_b32_e32 v9, v13
	v_permlane16_swap_b32_e32 v10, v14
	v_permlane16_swap_b32_e32 v11, v15
	v_permlane32_swap_b32_e32 v48, v52
	v_permlane32_swap_b32_e32 v49, v53
	v_permlane32_swap_b32_e32 v50, v54
	v_permlane32_swap_b32_e32 v51, v55
	v_permlane32_swap_b32_e32 v56, v60
	v_permlane32_swap_b32_e32 v57, v61
	v_permlane32_swap_b32_e32 v58, v62
	v_permlane32_swap_b32_e32 v59, v63
	v_permlane32_swap_b32_e32 v32, v36
	v_permlane32_swap_b32_e32 v33, v37
	v_permlane32_swap_b32_e32 v34, v38
	v_permlane32_swap_b32_e32 v35, v39
	v_permlane32_swap_b32_e32 v40, v44
	v_permlane32_swap_b32_e32 v41, v45
	v_permlane32_swap_b32_e32 v42, v46
	v_permlane32_swap_b32_e32 v43, v47
	v_permlane32_swap_b32_e32 v16, v20
	v_permlane32_swap_b32_e32 v17, v21
	v_permlane32_swap_b32_e32 v18, v22
	v_permlane32_swap_b32_e32 v19, v23
	v_permlane32_swap_b32_e32 v24, v28
	v_permlane32_swap_b32_e32 v25, v29
	v_permlane32_swap_b32_e32 v26, v30
	v_permlane32_swap_b32_e32 v27, v31
	v_permlane32_swap_b32_e32 v0, v4
	v_permlane32_swap_b32_e32 v1, v5
	v_permlane32_swap_b32_e32 v2, v6
	v_permlane32_swap_b32_e32 v3, v7
	v_permlane32_swap_b32_e32 v8, v12
	v_permlane32_swap_b32_e32 v9, v13
	v_permlane32_swap_b32_e32 v10, v14
	v_permlane32_swap_b32_e32 v11, v15
	s_setprio 0
	s_branch .LBB0_127

.LBB0_416:
	s_and_b32 s0, s0, 15
	s_or_b32 s18, s0, s50
	v_readlane_b32 s72, v250, 53
	s_lshl_b32 s0, s18, 18
	v_readlane_b32 s78, v250, 59
	v_readlane_b32 s79, v250, 60
	s_add_u32 s4, s78, s0
	v_mov_b32_e32 v3, v200
	v_readlane_b32 s80, v250, 61
	s_addc_u32 s5, s79, 0
	s_lshl_b32 s0, s17, 18
	v_ashrrev_i32_e32 v36, 3, v3
	v_lshlrev_b32_e32 v0, 3, v3
	v_readlane_b32 s81, v250, 62
	s_waitcnt vmcnt(0)
	v_and_b32_e32 v148, 56, v0
	s_add_u32 s6, s80, s0
	v_add_u32_e32 v40, 32, v36
	v_add_u32_e32 v44, 64, v36
	v_add_u32_e32 v48, 0x60, v36
	v_lshlrev_b32_e32 v196, 1, v148
	v_ashrrev_i32_e32 v37, 31, v36
	v_ashrrev_i32_e32 v41, 31, v40
	s_addc_u32 s7, s81, 0
	v_ashrrev_i32_e32 v45, 31, v44
	v_ashrrev_i32_e32 v49, 31, v48
	v_lshl_add_u64 v[128:129], s[4:5], 0, v[196:197]
	v_lshlrev_b64 v[130:131], 11, v[36:37]
	v_lshlrev_b64 v[132:133], 11, v[40:41]
	v_lshlrev_b64 v[134:135], 11, v[44:45]
	v_lshlrev_b64 v[136:137], 11, v[48:49]
	v_lshl_add_u64 v[138:139], s[6:7], 0, v[196:197]
	v_lshl_add_u64 v[38:39], v[128:129], 0, v[130:131]
	v_lshl_add_u64 v[42:43], v[128:129], 0, v[132:133]
	v_lshl_add_u64 v[46:47], v[128:129], 0, v[134:135]
	v_lshl_add_u64 v[50:51], v[128:129], 0, v[136:137]
	v_lshl_add_u64 v[52:53], v[138:139], 0, v[130:131]
	v_lshl_add_u64 v[54:55], v[138:139], 0, v[132:133]
	v_and_b32_e32 v184, 63, v200
	v_readfirstlane_b32 s2, v200
	v_lshrrev_b32_e32 v185, 3, v184
	v_and_b32_e32 v186, 7, v184
	v_lshrrev_b32_e32 v187, 4, v184
	s_lshr_b32 s2, s2, 6
	v_xor_b32_e32 v186, v186, v187
	v_lshlrev_b32_e32 v186, 4, v186
	v_xor_b32_e32 v187, 64, v186
	s_lshl_b32 s32, s2, 5
	v_add_u32_e32 v185, s32, v185
	v_lshlrev_b32_e32 v188, 11, v185
	v_add_u32_e32 v166, v188, v186
	v_add_u32_e32 v167, v188, v187
	v_add_u32_e32 v168, 0x8000, v166
	v_add_u32_e32 v169, 0x8000, v167
	v_add_u32_e32 v167, 0x4000, v167
	v_add_u32_e32 v169, 0x4000, v169
	v_and_b32_e32 v185, 15, v184
	v_lshrrev_b32_e32 v186, 4, v184
	v_bfe_u32 v187, v184, 1, 3
	v_xor_b32_e32 v186, v186, v187
	v_lshlrev_b32_e32 v186, 4, v186
	v_lshl_add_u32 v186, v185, 7, v186
	s_lshr_b32 s32, s2, 1
	s_lshl_b32 s32, s32, 13
	v_add_u32_e32 v170, s32, v186
	s_and_b32 s32, s2, 1
	s_lshl_b32 s32, s32, 13
	s_add_u32 s32, s32, 0x4000
	v_add_u32_e32 v174, s32, v186
	v_xor_b32_e32 v171, 64, v170
	v_xor_b32_e32 v175, 64, v174
	v_xor_b32_e32 v172, 64, v170
	v_xor_b32_e32 v176, 64, v174
	v_xor_b32_e32 v173, 96, v170
	v_xor_b32_e32 v177, 96, v174
	s_lshl_b32 s32, s2, 12
	s_add_u32 s49, s32, 0x4000
	s_mov_b32 s8, s4
	s_mov_b32 s9, s5
	s_mov_b32 s46, s6
	s_mov_b32 s47, s7
	s_add_u32 m0, s32, 0x0
	s_nop 0
	global_load_lds_dwordx4 v166, s[8:9]
	s_add_u32 m0, m0, 0x400
	s_nop 0
	global_load_lds_dwordx4 v167, s[8:9]
	s_add_u32 m0, m0, 0x400
	s_nop 0
	global_load_lds_dwordx4 v168, s[8:9]
	s_add_u32 m0, m0, 0x400
	s_nop 0
	global_load_lds_dwordx4 v169, s[8:9]
	s_add_u32 m0, s32, 0x4000
	s_nop 0
	global_load_lds_dwordx4 v166, s[46:47]
	s_add_u32 m0, m0, 0x400
	s_nop 0
	global_load_lds_dwordx4 v167, s[46:47]
	s_add_u32 m0, m0, 0x400
	s_nop 0
	global_load_lds_dwordx4 v168, s[46:47]
	s_add_u32 m0, m0, 0x400
	s_nop 0
	global_load_lds_dwordx4 v169, s[46:47]
	s_add_u32 s8, s8, 128
	s_addc_u32 s9, s9, 0
	s_add_u32 s46, s46, 128
	s_addc_u32 s47, s47, 0
	v_lshl_add_u64 v[56:57], v[138:139], 0, v[134:135]
	v_lshl_add_u64 v[58:59], v[138:139], 0, v[136:137]
	v_and_b32_e32 v60, 31, v3
	v_lshrrev_b32_e32 v61, 1, v3
	v_and_b32_e32 v3, 0x5f, v3
	s_movk_i32 s2, 0x90
	v_and_or_b32 v60, v61, s23, v60
	v_and_b32_e32 v61, 16, v61
	v_mad_u32_u24 v3, v3, s2, 0
	v_mul_lo_u32 v62, v36, s2
	v_mul_lo_u32 v60, v60, s2
	v_add_u32_e32 v149, v3, v61
	v_add_u32_e32 v3, 0, v196
	v_mov_b32_e32 v0, 0
	v_add_u32_e32 v63, 0x1200, v62
	v_lshlrev_b64 v[36:37], 10, v[36:37]
	v_lshlrev_b64 v[40:41], 10, v[40:41]
	v_lshlrev_b64 v[44:45], 10, v[44:45]
	v_lshlrev_b64 v[48:49], 10, v[48:49]
	v_add_u32_e32 v60, 0, v60
	v_add_u32_e32 v150, v3, v62
	s_movk_i32 s0, 0x80
	s_mov_b32 s1, 0
	v_mov_b32_e32 v1, v0
	v_mov_b32_e32 v2, v0
	v_lshlrev_b64 v[140:141], 1, v[36:37]
	v_add_u32_e32 v151, v3, v63
	v_lshlrev_b64 v[142:143], 1, v[40:41]
	v_lshlrev_b64 v[144:145], 1, v[44:45]
	v_lshlrev_b64 v[146:147], 1, v[48:49]
	v_add_u32_e32 v152, v60, v61
	v_mov_b32_e32 v3, v0
	v_mov_b32_e32 v36, v0
	v_mov_b32_e32 v37, v0
	v_mov_b32_e32 v38, v0
	v_mov_b32_e32 v39, v0
	v_mov_b32_e32 v40, v0
	v_mov_b32_e32 v41, v0
	v_mov_b32_e32 v42, v0
	v_mov_b32_e32 v43, v0
	v_mov_b32_e32 v44, v0
	v_mov_b32_e32 v45, v0
	v_mov_b32_e32 v46, v0
	v_mov_b32_e32 v47, v0
	v_mov_b32_e32 v4, v0
	v_mov_b32_e32 v5, v0
	v_mov_b32_e32 v6, v0
	v_mov_b32_e32 v7, v0
	v_mov_b32_e32 v8, v0
	v_mov_b32_e32 v9, v0
	v_mov_b32_e32 v10, v0
	v_mov_b32_e32 v11, v0
	v_mov_b32_e32 v12, v0
	v_mov_b32_e32 v13, v0
	v_mov_b32_e32 v14, v0
	v_mov_b32_e32 v15, v0
	v_mov_b32_e32 v16, v0
	v_mov_b32_e32 v17, v0
	v_mov_b32_e32 v18, v0
	v_mov_b32_e32 v19, v0
	v_mov_b32_e32 v20, v0
	v_mov_b32_e32 v21, v0
	v_mov_b32_e32 v22, v0
	v_mov_b32_e32 v23, v0
	v_mov_b32_e32 v24, v0
	v_mov_b32_e32 v25, v0
	v_mov_b32_e32 v26, v0
	v_mov_b32_e32 v27, v0
	v_mov_b32_e32 v28, v0
	v_mov_b32_e32 v29, v0
	v_mov_b32_e32 v30, v0
	v_mov_b32_e32 v31, v0
	v_mov_b32_e32 v32, v0
	v_mov_b32_e32 v33, v0
	v_mov_b32_e32 v34, v0
	v_mov_b32_e32 v35, v0
	v_mov_b32_e32 v48, v0
	v_mov_b32_e32 v49, v0
	v_mov_b32_e32 v50, v0
	v_mov_b32_e32 v51, v0
	v_mov_b32_e32 v52, v0
	v_mov_b32_e32 v53, v0
	v_mov_b32_e32 v54, v0
	v_mov_b32_e32 v55, v0
	v_mov_b32_e32 v56, v0
	v_mov_b32_e32 v57, v0
	v_mov_b32_e32 v58, v0
	v_mov_b32_e32 v59, v0
	v_mov_b32_e32 v60, v0
	v_mov_b32_e32 v61, v0
	v_mov_b32_e32 v62, v0
	v_mov_b32_e32 v63, v0
	v_readlane_b32 s73, v250, 54
	v_readlane_b32 s74, v250, 55
	v_readlane_b32 s75, v250, 56
	v_readlane_b32 s76, v250, 57
	v_readlane_b32 s77, v250, 58
	v_readlane_b32 s82, v250, 63
	v_readlane_b32 s83, v249, 0
	v_readlane_b32 s84, v249, 1
	v_readlane_b32 s85, v249, 2
	v_readlane_b32 s86, v249, 3
	v_readlane_b32 s87, v249, 4
	s_mov_b32 s0, 0x8000
	s_waitcnt vmcnt(0)
	s_waitcnt lgkmcnt(0)
	v_readlane_b32 s2, v251, 5
	s_nop 0
	s_bitcmp1_b32 s2, 5
	s_cbranch_scc0 .Lnoprio_3
	s_setprio 2

.LBB0_418:
	ds_read_b128 v[64:67], v174
	ds_read_b128 v[68:71], v170
	ds_read_b128 v[72:75], v174 offset:2048
	ds_read_b128 v[76:79], v170 offset:2048
	ds_read_b128 v[80:83], v174 offset:4096
	ds_read_b128 v[84:87], v174 offset:6144
	ds_read_b128 v[88:91], v170 offset:4096
	ds_read_b128 v[92:95], v170 offset:6144
	ds_read_b128 v[96:99], v175
	ds_read_b128 v[100:103], v171
	ds_read_b128 v[104:107], v175 offset:2048
	ds_read_b128 v[108:111], v171 offset:2048
	ds_read_b128 v[112:115], v175 offset:4096
	ds_read_b128 v[116:119], v175 offset:6144
	ds_read_b128 v[120:123], v171 offset:4096
	ds_read_b128 v[124:127], v171 offset:6144
	s_add_u32 m0, s32, s0
	s_nop 0
	global_load_lds_dwordx4 v166, s[8:9]
	s_add_u32 m0, m0, 0x400
	s_nop 0
	global_load_lds_dwordx4 v167, s[8:9]
	s_add_u32 m0, m0, 0x400
	s_nop 0
	global_load_lds_dwordx4 v168, s[8:9]
	s_add_u32 m0, m0, 0x400
	s_nop 0
	global_load_lds_dwordx4 v169, s[8:9]
	s_add_u32 m0, s49, s0
	s_nop 0
	global_load_lds_dwordx4 v166, s[46:47]
	s_add_u32 m0, m0, 0x400
	s_nop 0
	global_load_lds_dwordx4 v167, s[46:47]
	s_add_u32 m0, m0, 0x400
	s_nop 0
	global_load_lds_dwordx4 v168, s[46:47]
	s_add_u32 m0, m0, 0x400
	s_nop 0
	global_load_lds_dwordx4 v169, s[46:47]
	s_waitcnt lgkmcnt(14)
	v_mfma_f32_16x16x32_bf16 v[48:51], v[64:67], v[68:71], v[48:51]
	s_waitcnt lgkmcnt(13)
	v_mfma_f32_16x16x32_bf16 v[56:59], v[72:75], v[68:71], v[56:59]
	s_waitcnt lgkmcnt(12)
	v_mfma_f32_16x16x32_bf16 v[52:55], v[64:67], v[76:79], v[52:55]
	v_mfma_f32_16x16x32_bf16 v[60:63], v[72:75], v[76:79], v[60:63]
	s_waitcnt lgkmcnt(11)
	v_mfma_f32_16x16x32_bf16 v[32:35], v[80:83], v[68:71], v[32:35]
	v_mfma_f32_16x16x32_bf16 v[36:39], v[80:83], v[76:79], v[36:39]
	s_waitcnt lgkmcnt(10)
	v_mfma_f32_16x16x32_bf16 v[40:43], v[84:87], v[68:71], v[40:43]
	v_mfma_f32_16x16x32_bf16 v[44:47], v[84:87], v[76:79], v[44:47]
	s_waitcnt lgkmcnt(9)
	v_mfma_f32_16x16x32_bf16 v[16:19], v[64:67], v[88:91], v[16:19]
	v_mfma_f32_16x16x32_bf16 v[24:27], v[72:75], v[88:91], v[24:27]
	v_mfma_f32_16x16x32_bf16 v[0:3], v[80:83], v[88:91], v[0:3]
	v_mfma_f32_16x16x32_bf16 v[8:11], v[84:87], v[88:91], v[8:11]
	s_waitcnt lgkmcnt(8)
	v_mfma_f32_16x16x32_bf16 v[20:23], v[64:67], v[92:95], v[20:23]
	v_mfma_f32_16x16x32_bf16 v[28:31], v[72:75], v[92:95], v[28:31]
	v_mfma_f32_16x16x32_bf16 v[4:7], v[80:83], v[92:95], v[4:7]
	v_mfma_f32_16x16x32_bf16 v[12:15], v[84:87], v[92:95], v[12:15]
	s_waitcnt lgkmcnt(6)
	v_mfma_f32_16x16x32_bf16 v[48:51], v[96:99], v[100:103], v[48:51]
	s_waitcnt lgkmcnt(5)
	v_mfma_f32_16x16x32_bf16 v[56:59], v[104:107], v[100:103], v[56:59]
	s_waitcnt lgkmcnt(4)
	v_mfma_f32_16x16x32_bf16 v[52:55], v[96:99], v[108:111], v[52:55]
	v_mfma_f32_16x16x32_bf16 v[60:63], v[104:107], v[108:111], v[60:63]
	s_waitcnt lgkmcnt(3)
	v_mfma_f32_16x16x32_bf16 v[32:35], v[112:115], v[100:103], v[32:35]
	v_mfma_f32_16x16x32_bf16 v[36:39], v[112:115], v[108:111], v[36:39]
	s_waitcnt lgkmcnt(2)
	v_mfma_f32_16x16x32_bf16 v[40:43], v[116:119], v[100:103], v[40:43]
	v_mfma_f32_16x16x32_bf16 v[44:47], v[116:119], v[108:111], v[44:47]
	s_waitcnt lgkmcnt(1)
	v_mfma_f32_16x16x32_bf16 v[16:19], v[96:99], v[120:123], v[16:19]
	v_mfma_f32_16x16x32_bf16 v[24:27], v[104:107], v[120:123], v[24:27]
	v_mfma_f32_16x16x32_bf16 v[0:3], v[112:115], v[120:123], v[0:3]
	v_mfma_f32_16x16x32_bf16 v[8:11], v[116:119], v[120:123], v[8:11]
	s_waitcnt lgkmcnt(0)
	v_mfma_f32_16x16x32_bf16 v[20:23], v[96:99], v[124:127], v[20:23]
	v_mfma_f32_16x16x32_bf16 v[28:31], v[104:107], v[124:127], v[28:31]
	v_mfma_f32_16x16x32_bf16 v[4:7], v[112:115], v[124:127], v[4:7]
	v_mfma_f32_16x16x32_bf16 v[12:15], v[116:119], v[124:127], v[12:15]
	v_xor_b32_e32 v170, 0x8000, v170
	v_xor_b32_e32 v171, 0x8000, v171
	v_xor_b32_e32 v174, 0x8000, v174
	v_xor_b32_e32 v175, 0x8000, v175
	s_xor_b32 s0, s0, 0x8000
	s_add_u32 s8, s8, 128
	s_addc_u32 s9, s9, 0
	s_add_u32 s46, s46, 128
	s_addc_u32 s47, s47, 0
	s_add_u32 s1, s1, 1
	s_waitcnt vmcnt(0)
	s_cmp_lt_u32 s1, 15
	s_barrier
	s_cbranch_scc1 .LBB0_418
.Lp1z_tail:
	ds_read_b128 v[64:67], v174
	ds_read_b128 v[68:71], v170
	ds_read_b128 v[72:75], v174 offset:2048
	ds_read_b128 v[76:79], v170 offset:2048
	ds_read_b128 v[80:83], v174 offset:4096
	ds_read_b128 v[84:87], v174 offset:6144
	ds_read_b128 v[88:91], v170 offset:4096
	ds_read_b128 v[92:95], v170 offset:6144
	ds_read_b128 v[96:99], v175
	ds_read_b128 v[100:103], v171
	ds_read_b128 v[104:107], v175 offset:2048
	ds_read_b128 v[108:111], v171 offset:2048
	ds_read_b128 v[112:115], v175 offset:4096
	ds_read_b128 v[116:119], v175 offset:6144
	ds_read_b128 v[120:123], v171 offset:4096
	ds_read_b128 v[124:127], v171 offset:6144
	s_waitcnt lgkmcnt(14)
	v_mfma_f32_16x16x32_bf16 v[48:51], v[64:67], v[68:71], v[48:51]
	s_waitcnt lgkmcnt(13)
	v_mfma_f32_16x16x32_bf16 v[56:59], v[72:75], v[68:71], v[56:59]
	s_waitcnt lgkmcnt(12)
	v_mfma_f32_16x16x32_bf16 v[52:55], v[64:67], v[76:79], v[52:55]
	v_mfma_f32_16x16x32_bf16 v[60:63], v[72:75], v[76:79], v[60:63]
	s_waitcnt lgkmcnt(11)
	v_mfma_f32_16x16x32_bf16 v[32:35], v[80:83], v[68:71], v[32:35]
	v_mfma_f32_16x16x32_bf16 v[36:39], v[80:83], v[76:79], v[36:39]
	s_waitcnt lgkmcnt(10)
	v_mfma_f32_16x16x32_bf16 v[40:43], v[84:87], v[68:71], v[40:43]
	v_mfma_f32_16x16x32_bf16 v[44:47], v[84:87], v[76:79], v[44:47]
	s_waitcnt lgkmcnt(9)
	v_mfma_f32_16x16x32_bf16 v[16:19], v[64:67], v[88:91], v[16:19]
	v_mfma_f32_16x16x32_bf16 v[24:27], v[72:75], v[88:91], v[24:27]
	v_mfma_f32_16x16x32_bf16 v[0:3], v[80:83], v[88:91], v[0:3]
	v_mfma_f32_16x16x32_bf16 v[8:11], v[84:87], v[88:91], v[8:11]
	s_waitcnt lgkmcnt(8)
	v_mfma_f32_16x16x32_bf16 v[20:23], v[64:67], v[92:95], v[20:23]
	v_mfma_f32_16x16x32_bf16 v[28:31], v[72:75], v[92:95], v[28:31]
	v_mfma_f32_16x16x32_bf16 v[4:7], v[80:83], v[92:95], v[4:7]
	v_mfma_f32_16x16x32_bf16 v[12:15], v[84:87], v[92:95], v[12:15]
	s_waitcnt lgkmcnt(6)
	v_mfma_f32_16x16x32_bf16 v[48:51], v[96:99], v[100:103], v[48:51]
	s_waitcnt lgkmcnt(5)
	v_mfma_f32_16x16x32_bf16 v[56:59], v[104:107], v[100:103], v[56:59]
	s_waitcnt lgkmcnt(4)
	v_mfma_f32_16x16x32_bf16 v[52:55], v[96:99], v[108:111], v[52:55]
	v_mfma_f32_16x16x32_bf16 v[60:63], v[104:107], v[108:111], v[60:63]
	s_waitcnt lgkmcnt(3)
	v_mfma_f32_16x16x32_bf16 v[32:35], v[112:115], v[100:103], v[32:35]
	v_mfma_f32_16x16x32_bf16 v[36:39], v[112:115], v[108:111], v[36:39]
	s_waitcnt lgkmcnt(2)
	v_mfma_f32_16x16x32_bf16 v[40:43], v[116:119], v[100:103], v[40:43]
	v_mfma_f32_16x16x32_bf16 v[44:47], v[116:119], v[108:111], v[44:47]
	s_waitcnt lgkmcnt(1)
	v_mfma_f32_16x16x32_bf16 v[16:19], v[96:99], v[120:123], v[16:19]
	v_mfma_f32_16x16x32_bf16 v[24:27], v[104:107], v[120:123], v[24:27]
	v_mfma_f32_16x16x32_bf16 v[0:3], v[112:115], v[120:123], v[0:3]
	v_mfma_f32_16x16x32_bf16 v[8:11], v[116:119], v[120:123], v[8:11]
	s_waitcnt lgkmcnt(0)
	v_mfma_f32_16x16x32_bf16 v[20:23], v[96:99], v[124:127], v[20:23]
	v_mfma_f32_16x16x32_bf16 v[28:31], v[104:107], v[124:127], v[28:31]
	v_mfma_f32_16x16x32_bf16 v[4:7], v[112:115], v[124:127], v[4:7]
	v_mfma_f32_16x16x32_bf16 v[12:15], v[116:119], v[124:127], v[12:15]
	v_xor_b32_e32 v170, 0x8000, v170
	v_xor_b32_e32 v171, 0x8000, v171
	v_xor_b32_e32 v174, 0x8000, v174
	v_xor_b32_e32 v175, 0x8000, v175
	s_add_u32 s1, s1, 1
	s_waitcnt vmcnt(0)
	s_cmp_lt_u32 s1, 16
	s_barrier
	s_nop 7
	s_nop 7
	v_permlane16_swap_b32_e32 v48, v52
	v_permlane16_swap_b32_e32 v49, v53
	v_permlane16_swap_b32_e32 v50, v54
	v_permlane16_swap_b32_e32 v51, v55
	v_permlane16_swap_b32_e32 v56, v60
	v_permlane16_swap_b32_e32 v57, v61
	v_permlane16_swap_b32_e32 v58, v62
	v_permlane16_swap_b32_e32 v59, v63
	v_permlane16_swap_b32_e32 v32, v36
	v_permlane16_swap_b32_e32 v33, v37
	v_permlane16_swap_b32_e32 v34, v38
	v_permlane16_swap_b32_e32 v35, v39
	v_permlane16_swap_b32_e32 v40, v44
	v_permlane16_swap_b32_e32 v41, v45
	v_permlane16_swap_b32_e32 v42, v46
	v_permlane16_swap_b32_e32 v43, v47
	v_permlane16_swap_b32_e32 v16, v20
	v_permlane16_swap_b32_e32 v17, v21
	v_permlane16_swap_b32_e32 v18, v22
	v_permlane16_swap_b32_e32 v19, v23
	v_permlane16_swap_b32_e32 v24, v28
	v_permlane16_swap_b32_e32 v25, v29
	v_permlane16_swap_b32_e32 v26, v30
	v_permlane16_swap_b32_e32 v27, v31
	v_permlane16_swap_b32_e32 v0, v4
	v_permlane16_swap_b32_e32 v1, v5
	v_permlane16_swap_b32_e32 v2, v6
	v_permlane16_swap_b32_e32 v3, v7
	v_permlane16_swap_b32_e32 v8, v12
	v_permlane16_swap_b32_e32 v9, v13
	v_permlane16_swap_b32_e32 v10, v14
	v_permlane16_swap_b32_e32 v11, v15
	v_permlane32_swap_b32_e32 v48, v52
	v_permlane32_swap_b32_e32 v49, v53
	v_permlane32_swap_b32_e32 v50, v54
	v_permlane32_swap_b32_e32 v51, v55
	v_permlane32_swap_b32_e32 v56, v60
	v_permlane32_swap_b32_e32 v57, v61
	v_permlane32_swap_b32_e32 v58, v62
	v_permlane32_swap_b32_e32 v59, v63
	v_permlane32_swap_b32_e32 v32, v36
	v_permlane32_swap_b32_e32 v33, v37
	v_permlane32_swap_b32_e32 v34, v38
	v_permlane32_swap_b32_e32 v35, v39
	v_permlane32_swap_b32_e32 v40, v44
	v_permlane32_swap_b32_e32 v41, v45
	v_permlane32_swap_b32_e32 v42, v46
	v_permlane32_swap_b32_e32 v43, v47
	v_permlane32_swap_b32_e32 v16, v20
	v_permlane32_swap_b32_e32 v17, v21
	v_permlane32_swap_b32_e32 v18, v22
	v_permlane32_swap_b32_e32 v19, v23
	v_permlane32_swap_b32_e32 v24, v28
	v_permlane32_swap_b32_e32 v25, v29
	v_permlane32_swap_b32_e32 v26, v30
	v_permlane32_swap_b32_e32 v27, v31
	v_permlane32_swap_b32_e32 v0, v4
	v_permlane32_swap_b32_e32 v1, v5
	v_permlane32_swap_b32_e32 v2, v6
	v_permlane32_swap_b32_e32 v3, v7
	v_permlane32_swap_b32_e32 v8, v12
	v_permlane32_swap_b32_e32 v9, v13
	v_permlane32_swap_b32_e32 v10, v14
	v_permlane32_swap_b32_e32 v11, v15
	s_setprio 0
	s_branch .LBB0_420

.LBB0_448:
	s_ashr_i32 s6, s12, 3
	s_ashr_i32 s7, s6, 31
	s_and_b32 s1, s12, 7
	s_lshl_b64 s[4:5], s[6:7], 17
	s_lshl_b64 s[6:7], s[6:7], 18
	s_add_u32 s6, s56, s6
	v_readlane_b32 s16, v250, 53
	v_mov_b32_e32 v1, v200
	s_addc_u32 s7, s57, s7
	s_lshl_b32 s2, s1, 18
	v_readlane_b32 s30, v249, 3
	v_readlane_b32 s31, v249, 4
	v_ashrrev_i32_e32 v34, 3, v1
	v_lshlrev_b32_e32 v0, 3, v1
	s_add_u32 s8, s30, s2
	s_waitcnt vmcnt(0)
	v_and_b32_e32 v148, 56, v0
	v_add_u32_e32 v40, 32, v34
	v_add_u32_e32 v46, 64, v34
	v_add_u32_e32 v50, 0x60, v34
	s_addc_u32 s9, s31, 0
	v_lshlrev_b32_e32 v196, 1, v148
	v_ashrrev_i32_e32 v35, 31, v34
	v_ashrrev_i32_e32 v41, 31, v40
	v_ashrrev_i32_e32 v47, 31, v46
	v_ashrrev_i32_e32 v51, 31, v50
	v_lshl_add_u64 v[128:129], s[6:7], 0, v[196:197]
	v_lshl_add_u64 v[130:131], s[8:9], 0, v[196:197]
	v_lshlrev_b64 v[132:133], 11, v[34:35]
	v_lshlrev_b64 v[134:135], 11, v[40:41]
	v_lshlrev_b64 v[136:137], 11, v[46:47]
	v_lshlrev_b64 v[138:139], 11, v[50:51]
	v_lshl_add_u64 v[36:37], v[128:129], 0, v[132:133]
	v_lshl_add_u64 v[38:39], v[130:131], 0, v[132:133]
	v_lshl_add_u64 v[42:43], v[128:129], 0, v[134:135]
	v_lshl_add_u64 v[44:45], v[130:131], 0, v[134:135]
	v_lshl_add_u64 v[48:49], v[128:129], 0, v[136:137]
	v_lshl_add_u64 v[52:53], v[128:129], 0, v[138:139]
	v_lshl_add_u64 v[54:55], v[130:131], 0, v[136:137]
	v_lshl_add_u64 v[56:57], v[130:131], 0, v[138:139]
	v_and_b32_e32 v184, 63, v200
	v_readfirstlane_b32 s2, v200
	v_lshrrev_b32_e32 v185, 3, v184
	v_and_b32_e32 v186, 7, v184
	v_lshrrev_b32_e32 v187, 4, v184
	s_lshr_b32 s2, s2, 6
	v_xor_b32_e32 v186, v186, v187
	v_lshlrev_b32_e32 v186, 4, v186
	v_xor_b32_e32 v187, 64, v186
	s_lshl_b32 s32, s2, 5
	v_add_u32_e32 v185, s32, v185
	v_lshlrev_b32_e32 v188, 11, v185
	v_add_u32_e32 v166, v188, v186
	v_add_u32_e32 v167, v188, v187
	v_add_u32_e32 v168, 0x8000, v166
	v_add_u32_e32 v169, 0x8000, v167
	v_add_u32_e32 v167, 0x4000, v167
	v_add_u32_e32 v169, 0x4000, v169
	v_and_b32_e32 v185, 15, v184
	v_lshrrev_b32_e32 v186, 4, v184
	v_bfe_u32 v187, v184, 1, 3
	v_xor_b32_e32 v186, v186, v187
	v_lshlrev_b32_e32 v186, 4, v186
	v_lshl_add_u32 v186, v185, 7, v186
	s_lshr_b32 s32, s2, 1
	s_lshl_b32 s32, s32, 13
	v_add_u32_e32 v170, s32, v186
	s_and_b32 s32, s2, 1
	s_lshl_b32 s32, s32, 13
	s_add_u32 s32, s32, 0x4000
	v_add_u32_e32 v174, s32, v186
	v_xor_b32_e32 v171, 64, v170
	v_xor_b32_e32 v175, 64, v174
	v_xor_b32_e32 v172, 64, v170
	v_xor_b32_e32 v176, 64, v174
	v_xor_b32_e32 v173, 96, v170
	v_xor_b32_e32 v177, 96, v174
	s_lshl_b32 s32, s2, 12
	s_add_u32 s49, s32, 0x4000
	s_mov_b32 s10, s6
	s_mov_b32 s11, s7
	s_mov_b32 s46, s8
	s_mov_b32 s47, s9
	s_add_u32 m0, s32, 0x0
	s_nop 0
	global_load_lds_dwordx4 v166, s[10:11]
	s_add_u32 m0, m0, 0x400
	s_nop 0
	global_load_lds_dwordx4 v167, s[10:11]
	s_add_u32 m0, m0, 0x400
	s_nop 0
	global_load_lds_dwordx4 v168, s[10:11]
	s_add_u32 m0, m0, 0x400
	s_nop 0
	global_load_lds_dwordx4 v169, s[10:11]
	s_add_u32 m0, s32, 0x4000
	s_nop 0
	global_load_lds_dwordx4 v166, s[46:47]
	s_add_u32 m0, m0, 0x400
	s_nop 0
	global_load_lds_dwordx4 v167, s[46:47]
	s_add_u32 m0, m0, 0x400
	s_nop 0
	global_load_lds_dwordx4 v168, s[46:47]
	s_add_u32 m0, m0, 0x400
	s_nop 0
	global_load_lds_dwordx4 v169, s[46:47]
	s_add_u32 s10, s10, 128
	s_addc_u32 s11, s11, 0
	s_add_u32 s46, s46, 128
	s_addc_u32 s47, s47, 0
	v_and_b32_e32 v58, 31, v1
	v_lshrrev_b32_e32 v59, 1, v1
	v_and_b32_e32 v1, 0x5f, v1
	s_movk_i32 s2, 0x90
	v_and_or_b32 v58, v59, s10, v58
	v_and_b32_e32 v59, 16, v59
	v_mad_u32_u24 v1, v1, s2, 0
	v_mul_lo_u32 v60, v34, s2
	v_mul_lo_u32 v58, v58, s2
	v_add_u32_e32 v149, v1, v59
	v_add_u32_e32 v1, 0, v196
	v_mov_b32_e32 v0, 0
	v_lshlrev_b64 v[34:35], 10, v[34:35]
	v_add_u32_e32 v61, 0x1200, v60
	v_lshlrev_b64 v[40:41], 10, v[40:41]
	v_lshlrev_b64 v[46:47], 10, v[46:47]
	v_lshlrev_b64 v[50:51], 10, v[50:51]
	v_add_u32_e32 v58, 0, v58
	v_add_u32_e32 v150, v1, v60
	s_mov_b32 s13, 0
	s_movk_i32 s14, 0x80
	v_lshlrev_b64 v[140:141], 1, v[34:35]
	v_add_u32_e32 v151, v1, v61
	v_lshlrev_b64 v[142:143], 1, v[40:41]
	v_lshlrev_b64 v[144:145], 1, v[46:47]
	v_lshlrev_b64 v[146:147], 1, v[50:51]
	v_add_u32_e32 v152, v58, v59
	v_mov_b32_e32 v1, v0
	v_mov_b32_e32 v34, v0
	v_mov_b32_e32 v35, v0
	v_mov_b32_e32 v36, v0
	v_mov_b32_e32 v37, v0
	v_mov_b32_e32 v38, v0
	v_mov_b32_e32 v39, v0
	v_mov_b32_e32 v40, v0
	v_mov_b32_e32 v41, v0
	v_mov_b32_e32 v42, v0
	v_mov_b32_e32 v43, v0
	v_mov_b32_e32 v2, v0
	v_mov_b32_e32 v3, v0
	v_mov_b32_e32 v4, v0
	v_mov_b32_e32 v5, v0
	v_mov_b32_e32 v6, v0
	v_mov_b32_e32 v7, v0
	v_mov_b32_e32 v8, v0
	v_mov_b32_e32 v9, v0
	v_mov_b32_e32 v10, v0
	v_mov_b32_e32 v11, v0
	v_mov_b32_e32 v12, v0
	v_mov_b32_e32 v13, v0
	v_mov_b32_e32 v14, v0
	v_mov_b32_e32 v15, v0
	v_mov_b32_e32 v16, v0
	v_mov_b32_e32 v17, v0
	v_mov_b32_e32 v18, v0
	v_mov_b32_e32 v19, v0
	v_mov_b32_e32 v20, v0
	v_mov_b32_e32 v21, v0
	v_mov_b32_e32 v22, v0
	v_mov_b32_e32 v23, v0
	v_mov_b32_e32 v24, v0
	v_mov_b32_e32 v25, v0
	v_mov_b32_e32 v26, v0
	v_mov_b32_e32 v27, v0
	v_mov_b32_e32 v28, v0
	v_mov_b32_e32 v29, v0
	v_mov_b32_e32 v30, v0
	v_mov_b32_e32 v31, v0
	v_mov_b32_e32 v32, v0
	v_mov_b32_e32 v33, v0
	v_mov_b32_e32 v44, v0
	v_mov_b32_e32 v45, v0
	v_mov_b32_e32 v46, v0
	v_mov_b32_e32 v47, v0
	v_mov_b32_e32 v48, v0
	v_mov_b32_e32 v49, v0
	v_mov_b32_e32 v50, v0
	v_mov_b32_e32 v51, v0
	v_mov_b32_e32 v52, v0
	v_mov_b32_e32 v53, v0
	v_mov_b32_e32 v54, v0
	v_mov_b32_e32 v55, v0
	v_mov_b32_e32 v56, v0
	v_mov_b32_e32 v57, v0
	v_mov_b32_e32 v58, v0
	v_mov_b32_e32 v59, v0
	v_mov_b32_e32 v60, v0
	v_mov_b32_e32 v61, v0
	v_mov_b32_e32 v62, v0
	v_mov_b32_e32 v63, v0
	s_mov_b32 s15, 0xfffffc0
	v_readlane_b32 s17, v250, 54
	v_readlane_b32 s18, v250, 55
	v_readlane_b32 s19, v250, 56
	v_readlane_b32 s20, v250, 57
	v_readlane_b32 s21, v250, 58
	v_readlane_b32 s22, v250, 59
	v_readlane_b32 s23, v250, 60
	v_readlane_b32 s24, v250, 61
	v_readlane_b32 s25, v250, 62
	v_readlane_b32 s26, v250, 63
	v_readlane_b32 s27, v249, 0
	v_readlane_b32 s28, v249, 1
	v_readlane_b32 s29, v249, 2
	s_mov_b32 s14, 0x8000
	s_waitcnt vmcnt(0)
	s_waitcnt lgkmcnt(0)
	v_readlane_b32 s2, v251, 5
	s_nop 0
	s_bitcmp1_b32 s2, 5
	s_cbranch_scc0 .Lnoprio_4
	s_setprio 2

.LBB0_450:
	ds_read_b128 v[64:67], v174
	ds_read_b128 v[68:71], v170
	ds_read_b128 v[72:75], v174 offset:2048
	ds_read_b128 v[76:79], v170 offset:2048
	ds_read_b128 v[80:83], v174 offset:4096
	ds_read_b128 v[84:87], v174 offset:6144
	ds_read_b128 v[88:91], v170 offset:4096
	ds_read_b128 v[92:95], v170 offset:6144
	ds_read_b128 v[96:99], v175
	ds_read_b128 v[100:103], v171
	ds_read_b128 v[104:107], v175 offset:2048
	ds_read_b128 v[108:111], v171 offset:2048
	ds_read_b128 v[112:115], v175 offset:4096
	ds_read_b128 v[116:119], v175 offset:6144
	ds_read_b128 v[120:123], v171 offset:4096
	ds_read_b128 v[124:127], v171 offset:6144
	s_add_u32 m0, s32, s14
	s_nop 0
	global_load_lds_dwordx4 v166, s[10:11]
	s_add_u32 m0, m0, 0x400
	s_nop 0
	global_load_lds_dwordx4 v167, s[10:11]
	s_add_u32 m0, m0, 0x400
	s_nop 0
	global_load_lds_dwordx4 v168, s[10:11]
	s_add_u32 m0, m0, 0x400
	s_nop 0
	global_load_lds_dwordx4 v169, s[10:11]
	s_add_u32 m0, s49, s14
	s_nop 0
	global_load_lds_dwordx4 v166, s[46:47]
	s_add_u32 m0, m0, 0x400
	s_nop 0
	global_load_lds_dwordx4 v167, s[46:47]
	s_add_u32 m0, m0, 0x400
	s_nop 0
	global_load_lds_dwordx4 v168, s[46:47]
	s_add_u32 m0, m0, 0x400
	s_nop 0
	global_load_lds_dwordx4 v169, s[46:47]
	s_waitcnt lgkmcnt(14)
	v_mfma_f32_16x16x32_bf16 v[48:51], v[64:67], v[68:71], v[48:51]
	s_waitcnt lgkmcnt(13)
	v_mfma_f32_16x16x32_bf16 v[56:59], v[72:75], v[68:71], v[56:59]
	s_waitcnt lgkmcnt(12)
	v_mfma_f32_16x16x32_bf16 v[52:55], v[64:67], v[76:79], v[52:55]
	v_mfma_f32_16x16x32_bf16 v[60:63], v[72:75], v[76:79], v[60:63]
	s_waitcnt lgkmcnt(11)
	v_mfma_f32_16x16x32_bf16 v[32:35], v[80:83], v[68:71], v[32:35]
	v_mfma_f32_16x16x32_bf16 v[36:39], v[80:83], v[76:79], v[36:39]
	s_waitcnt lgkmcnt(10)
	v_mfma_f32_16x16x32_bf16 v[40:43], v[84:87], v[68:71], v[40:43]
	v_mfma_f32_16x16x32_bf16 v[44:47], v[84:87], v[76:79], v[44:47]
	s_waitcnt lgkmcnt(9)
	v_mfma_f32_16x16x32_bf16 v[16:19], v[64:67], v[88:91], v[16:19]
	v_mfma_f32_16x16x32_bf16 v[24:27], v[72:75], v[88:91], v[24:27]
	v_mfma_f32_16x16x32_bf16 v[0:3], v[80:83], v[88:91], v[0:3]
	v_mfma_f32_16x16x32_bf16 v[8:11], v[84:87], v[88:91], v[8:11]
	s_waitcnt lgkmcnt(8)
	v_mfma_f32_16x16x32_bf16 v[20:23], v[64:67], v[92:95], v[20:23]
	v_mfma_f32_16x16x32_bf16 v[28:31], v[72:75], v[92:95], v[28:31]
	v_mfma_f32_16x16x32_bf16 v[4:7], v[80:83], v[92:95], v[4:7]
	v_mfma_f32_16x16x32_bf16 v[12:15], v[84:87], v[92:95], v[12:15]
	s_waitcnt lgkmcnt(6)
	v_mfma_f32_16x16x32_bf16 v[48:51], v[96:99], v[100:103], v[48:51]
	s_waitcnt lgkmcnt(5)
	v_mfma_f32_16x16x32_bf16 v[56:59], v[104:107], v[100:103], v[56:59]
	s_waitcnt lgkmcnt(4)
	v_mfma_f32_16x16x32_bf16 v[52:55], v[96:99], v[108:111], v[52:55]
	v_mfma_f32_16x16x32_bf16 v[60:63], v[104:107], v[108:111], v[60:63]
	s_waitcnt lgkmcnt(3)
	v_mfma_f32_16x16x32_bf16 v[32:35], v[112:115], v[100:103], v[32:35]
	v_mfma_f32_16x16x32_bf16 v[36:39], v[112:115], v[108:111], v[36:39]
	s_waitcnt lgkmcnt(2)
	v_mfma_f32_16x16x32_bf16 v[40:43], v[116:119], v[100:103], v[40:43]
	v_mfma_f32_16x16x32_bf16 v[44:47], v[116:119], v[108:111], v[44:47]
	s_waitcnt lgkmcnt(1)
	v_mfma_f32_16x16x32_bf16 v[16:19], v[96:99], v[120:123], v[16:19]
	v_mfma_f32_16x16x32_bf16 v[24:27], v[104:107], v[120:123], v[24:27]
	v_mfma_f32_16x16x32_bf16 v[0:3], v[112:115], v[120:123], v[0:3]
	v_mfma_f32_16x16x32_bf16 v[8:11], v[116:119], v[120:123], v[8:11]
	s_waitcnt lgkmcnt(0)
	v_mfma_f32_16x16x32_bf16 v[20:23], v[96:99], v[124:127], v[20:23]
	v_mfma_f32_16x16x32_bf16 v[28:31], v[104:107], v[124:127], v[28:31]
	v_mfma_f32_16x16x32_bf16 v[4:7], v[112:115], v[124:127], v[4:7]
	v_mfma_f32_16x16x32_bf16 v[12:15], v[116:119], v[124:127], v[12:15]
	v_xor_b32_e32 v170, 0x8000, v170
	v_xor_b32_e32 v171, 0x8000, v171
	v_xor_b32_e32 v174, 0x8000, v174
	v_xor_b32_e32 v175, 0x8000, v175
	s_xor_b32 s14, s14, 0x8000
	s_add_u32 s10, s10, 128
	s_addc_u32 s11, s11, 0
	s_add_u32 s46, s46, 128
	s_addc_u32 s47, s47, 0
	s_add_u32 s13, s13, 1
	s_waitcnt vmcnt(0)
	s_cmp_lt_u32 s13, 15
	s_barrier
	s_cbranch_scc1 .LBB0_450
.Lp1k_tail:
	ds_read_b128 v[64:67], v174
	ds_read_b128 v[68:71], v170
	ds_read_b128 v[72:75], v174 offset:2048
	ds_read_b128 v[76:79], v170 offset:2048
	ds_read_b128 v[80:83], v174 offset:4096
	ds_read_b128 v[84:87], v174 offset:6144
	ds_read_b128 v[88:91], v170 offset:4096
	ds_read_b128 v[92:95], v170 offset:6144
	ds_read_b128 v[96:99], v175
	ds_read_b128 v[100:103], v171
	ds_read_b128 v[104:107], v175 offset:2048
	ds_read_b128 v[108:111], v171 offset:2048
	ds_read_b128 v[112:115], v175 offset:4096
	ds_read_b128 v[116:119], v175 offset:6144
	ds_read_b128 v[120:123], v171 offset:4096
	ds_read_b128 v[124:127], v171 offset:6144
	s_waitcnt lgkmcnt(14)
	v_mfma_f32_16x16x32_bf16 v[48:51], v[64:67], v[68:71], v[48:51]
	s_waitcnt lgkmcnt(13)
	v_mfma_f32_16x16x32_bf16 v[56:59], v[72:75], v[68:71], v[56:59]
	s_waitcnt lgkmcnt(12)
	v_mfma_f32_16x16x32_bf16 v[52:55], v[64:67], v[76:79], v[52:55]
	v_mfma_f32_16x16x32_bf16 v[60:63], v[72:75], v[76:79], v[60:63]
	s_waitcnt lgkmcnt(11)
	v_mfma_f32_16x16x32_bf16 v[32:35], v[80:83], v[68:71], v[32:35]
	v_mfma_f32_16x16x32_bf16 v[36:39], v[80:83], v[76:79], v[36:39]
	s_waitcnt lgkmcnt(10)
	v_mfma_f32_16x16x32_bf16 v[40:43], v[84:87], v[68:71], v[40:43]
	v_mfma_f32_16x16x32_bf16 v[44:47], v[84:87], v[76:79], v[44:47]
	s_waitcnt lgkmcnt(9)
	v_mfma_f32_16x16x32_bf16 v[16:19], v[64:67], v[88:91], v[16:19]
	v_mfma_f32_16x16x32_bf16 v[24:27], v[72:75], v[88:91], v[24:27]
	v_mfma_f32_16x16x32_bf16 v[0:3], v[80:83], v[88:91], v[0:3]
	v_mfma_f32_16x16x32_bf16 v[8:11], v[84:87], v[88:91], v[8:11]
	s_waitcnt lgkmcnt(8)
	v_mfma_f32_16x16x32_bf16 v[20:23], v[64:67], v[92:95], v[20:23]
	v_mfma_f32_16x16x32_bf16 v[28:31], v[72:75], v[92:95], v[28:31]
	v_mfma_f32_16x16x32_bf16 v[4:7], v[80:83], v[92:95], v[4:7]
	v_mfma_f32_16x16x32_bf16 v[12:15], v[84:87], v[92:95], v[12:15]
	s_waitcnt lgkmcnt(6)
	v_mfma_f32_16x16x32_bf16 v[48:51], v[96:99], v[100:103], v[48:51]
	s_waitcnt lgkmcnt(5)
	v_mfma_f32_16x16x32_bf16 v[56:59], v[104:107], v[100:103], v[56:59]
	s_waitcnt lgkmcnt(4)
	v_mfma_f32_16x16x32_bf16 v[52:55], v[96:99], v[108:111], v[52:55]
	v_mfma_f32_16x16x32_bf16 v[60:63], v[104:107], v[108:111], v[60:63]
	s_waitcnt lgkmcnt(3)
	v_mfma_f32_16x16x32_bf16 v[32:35], v[112:115], v[100:103], v[32:35]
	v_mfma_f32_16x16x32_bf16 v[36:39], v[112:115], v[108:111], v[36:39]
	s_waitcnt lgkmcnt(2)
	v_mfma_f32_16x16x32_bf16 v[40:43], v[116:119], v[100:103], v[40:43]
	v_mfma_f32_16x16x32_bf16 v[44:47], v[116:119], v[108:111], v[44:47]
	s_waitcnt lgkmcnt(1)
	v_mfma_f32_16x16x32_bf16 v[16:19], v[96:99], v[120:123], v[16:19]
	v_mfma_f32_16x16x32_bf16 v[24:27], v[104:107], v[120:123], v[24:27]
	v_mfma_f32_16x16x32_bf16 v[0:3], v[112:115], v[120:123], v[0:3]
	v_mfma_f32_16x16x32_bf16 v[8:11], v[116:119], v[120:123], v[8:11]
	s_waitcnt lgkmcnt(0)
	v_mfma_f32_16x16x32_bf16 v[20:23], v[96:99], v[124:127], v[20:23]
	v_mfma_f32_16x16x32_bf16 v[28:31], v[104:107], v[124:127], v[28:31]
	v_mfma_f32_16x16x32_bf16 v[4:7], v[112:115], v[124:127], v[4:7]
	v_mfma_f32_16x16x32_bf16 v[12:15], v[116:119], v[124:127], v[12:15]
	v_xor_b32_e32 v170, 0x8000, v170
	v_xor_b32_e32 v171, 0x8000, v171
	v_xor_b32_e32 v174, 0x8000, v174
	v_xor_b32_e32 v175, 0x8000, v175
	s_add_u32 s13, s13, 1
	s_waitcnt vmcnt(0)
	s_cmp_lt_u32 s13, 16
	s_barrier
	s_nop 7
	s_nop 7
	v_permlane16_swap_b32_e32 v48, v52
	v_permlane16_swap_b32_e32 v49, v53
	v_permlane16_swap_b32_e32 v50, v54
	v_permlane16_swap_b32_e32 v51, v55
	v_permlane16_swap_b32_e32 v56, v60
	v_permlane16_swap_b32_e32 v57, v61
	v_permlane16_swap_b32_e32 v58, v62
	v_permlane16_swap_b32_e32 v59, v63
	v_permlane16_swap_b32_e32 v32, v36
	v_permlane16_swap_b32_e32 v33, v37
	v_permlane16_swap_b32_e32 v34, v38
	v_permlane16_swap_b32_e32 v35, v39
	v_permlane16_swap_b32_e32 v40, v44
	v_permlane16_swap_b32_e32 v41, v45
	v_permlane16_swap_b32_e32 v42, v46
	v_permlane16_swap_b32_e32 v43, v47
	v_permlane16_swap_b32_e32 v16, v20
	v_permlane16_swap_b32_e32 v17, v21
	v_permlane16_swap_b32_e32 v18, v22
	v_permlane16_swap_b32_e32 v19, v23
	v_permlane16_swap_b32_e32 v24, v28
	v_permlane16_swap_b32_e32 v25, v29
	v_permlane16_swap_b32_e32 v26, v30
	v_permlane16_swap_b32_e32 v27, v31
	v_permlane16_swap_b32_e32 v0, v4
	v_permlane16_swap_b32_e32 v1, v5
	v_permlane16_swap_b32_e32 v2, v6
	v_permlane16_swap_b32_e32 v3, v7
	v_permlane16_swap_b32_e32 v8, v12
	v_permlane16_swap_b32_e32 v9, v13
	v_permlane16_swap_b32_e32 v10, v14
	v_permlane16_swap_b32_e32 v11, v15
	v_permlane32_swap_b32_e32 v48, v52
	v_permlane32_swap_b32_e32 v49, v53
	v_permlane32_swap_b32_e32 v50, v54
	v_permlane32_swap_b32_e32 v51, v55
	v_permlane32_swap_b32_e32 v56, v60
	v_permlane32_swap_b32_e32 v57, v61
	v_permlane32_swap_b32_e32 v58, v62
	v_permlane32_swap_b32_e32 v59, v63
	v_permlane32_swap_b32_e32 v32, v36
	v_permlane32_swap_b32_e32 v33, v37
	v_permlane32_swap_b32_e32 v34, v38
	v_permlane32_swap_b32_e32 v35, v39
	v_permlane32_swap_b32_e32 v40, v44
	v_permlane32_swap_b32_e32 v41, v45
	v_permlane32_swap_b32_e32 v42, v46
	v_permlane32_swap_b32_e32 v43, v47
	v_permlane32_swap_b32_e32 v16, v20
	v_permlane32_swap_b32_e32 v17, v21
	v_permlane32_swap_b32_e32 v18, v22
	v_permlane32_swap_b32_e32 v19, v23
	v_permlane32_swap_b32_e32 v24, v28
	v_permlane32_swap_b32_e32 v25, v29
	v_permlane32_swap_b32_e32 v26, v30
	v_permlane32_swap_b32_e32 v27, v31
	v_permlane32_swap_b32_e32 v0, v4
	v_permlane32_swap_b32_e32 v1, v5
	v_permlane32_swap_b32_e32 v2, v6
	v_permlane32_swap_b32_e32 v3, v7
	v_permlane32_swap_b32_e32 v8, v12
	v_permlane32_swap_b32_e32 v9, v13
	v_permlane32_swap_b32_e32 v10, v14
	v_permlane32_swap_b32_e32 v11, v15
	s_setprio 0
	s_branch .LBB0_447
